# weight transposition prologue: next tile's row loads issued right after the current tile is written to LDS (register double buffer)
# baseline (speedup 1.0000x reference)
.LBB0_27:
	v_readlane_b32 s4, v250, 30
	v_readlane_b32 s5, v250, 31
	v_mov_b32_e32 v4, v0
	s_mul_i32 s84, s26, 0x1800000
	s_mov_b64 s[0:1], 0
	s_andn2_b64 vcc, exec, s[4:5]
	s_cbranch_vccnz .LBB0_34
	v_readlane_b32 s8, v250, 41
	v_readlane_b32 s10, v250, 43
	v_readlane_b32 s9, v250, 42
	v_readlane_b32 s11, v250, 44
	s_add_u32 s4, s10, s84
	s_addc_u32 s5, s11, 0
	v_readlane_b32 s8, v250, 0
	v_readlane_b32 s10, v250, 2
	v_readlane_b32 s11, v250, 3
	s_add_u32 s0, s10, s0
	s_addc_u32 s1, s11, s1
	s_mul_i32 s6, s26, 0x600000
	s_add_u32 s0, s0, s6
	s_addc_u32 s1, s1, 0
	v_lshlrev_b32_e32 v2, 2, v4
	s_add_u32 s6, s0, 0x2bfe6000
	v_and_b32_e32 v7, 60, v2
	v_ashrrev_i32_e32 v2, 8, v4
	v_readlane_b32 s0, v250, 27
	v_lshl_add_u32 v5, v2, 16, 0
	v_lshlrev_b32_e32 v10, 1, v4
	v_add_u32_e32 v9, s0, v2
	v_lshlrev_b32_e32 v2, 4, v4
	v_and_b32_e32 v2, 48, v2
	v_bfe_u32 v6, v4, 4, 4
	v_bfe_u32 v8, v4, 2, 6
	v_and_b32_e32 v10, 16, v10
	v_lshlrev_b32_e32 v4, 3, v4
	v_mul_u32_u24_e32 v11, 0x44, v2
	v_and_or_b32 v10, v4, 32, v10
	v_mul_u32_u24_e32 v4, 0x44, v6
	v_or_b32_e32 v11, v11, v8
	v_add_lshl_u32 v4, v4, v7, 2
	v_lshlrev_b32_e32 v16, 2, v11
	v_add_u32_e32 v13, 0x1100, v4
	v_add_u32_e32 v14, 0x2200, v4
	v_add_u32_e32 v15, 0x3300, v4
	v_add_u32_e32 v17, 0x110, v16
	v_add_u32_e32 v18, 0x220, v16
	v_add_u32_e32 v19, 0x330, v16
	v_add_u32_e32 v26, 0x440, v16
	v_add_u32_e32 v27, 0x550, v16
	v_add_u32_e32 v28, 0x660, v16
	v_add_u32_e32 v29, 0x770, v16
	v_add_u32_e32 v30, 0x880, v16
	v_add_u32_e32 v31, 0x990, v16
	v_add_u32_e32 v32, 0xaa0, v16
	v_add_u32_e32 v33, 0xbb0, v16
	v_add_u32_e32 v34, 0xcc0, v16
	v_add_u32_e32 v35, 0xdd0, v16
	v_add_u32_e32 v36, 0xee0, v16
	v_add_u32_e32 v37, 0xff0, v16
	s_addc_u32 s7, s1, 0
	v_lshlrev_b32_e32 v11, 6, v9
	s_lshl_b32 s10, s3, 6
	v_add_u32_e32 v12, v5, v4
	v_add_u32_e32 v13, v5, v13
	v_add_u32_e32 v14, v5, v14
	v_add_u32_e32 v15, v5, v15
	v_add_u32_e32 v16, v5, v16
	v_add_u32_e32 v17, v5, v17
	v_add_u32_e32 v18, v5, v18
	v_add_u32_e32 v19, v5, v19
	v_add_u32_e32 v26, v5, v26
	v_add_u32_e32 v27, v5, v27
	v_add_u32_e32 v28, v5, v28
	v_add_u32_e32 v29, v5, v29
	v_add_u32_e32 v30, v5, v30
	v_add_u32_e32 v31, v5, v31
	v_add_u32_e32 v32, v5, v32
	v_add_u32_e32 v33, v5, v33
	v_add_u32_e32 v34, v5, v34
	v_add_u32_e32 v35, v5, v35
	v_add_u32_e32 v36, v5, v36
	v_add_u32_e32 v37, v5, v37
	v_readlane_b32 s11, v250, 28
	v_readlane_b32 s12, v250, 45
	v_readlane_b32 s13, v250, 46
	v_readlane_b32 s14, v250, 47
	v_readlane_b32 s15, v250, 48
	v_readlane_b32 s16, v250, 49
	v_readlane_b32 s17, v250, 50
	v_readlane_b32 s18, v250, 51
	v_readlane_b32 s19, v250, 52
	v_readlane_b32 s20, v250, 53
	v_readlane_b32 s21, v250, 54
	v_readlane_b32 s22, v250, 55
	v_readlane_b32 s23, v250, 56
	v_readlane_b32 s9, v250, 1
	v_mov_b32_e32 v109, v9
	v_mov_b32_e32 v111, v11
	v_mul_hi_i32 v104, v109, s58
	s_movk_i32 s0, 0x600
	v_lshrrev_b32_e32 v105, 31, v104
	v_ashrrev_i32_e32 v104, 3, v104
	v_cmp_gt_i32_e64 s[98:99], s0, v109
	v_add_u32_e32 v104, v104, v105
	s_movk_i32 s0, 0xf400
	v_mul_lo_u32 v105, v104, s0
	v_lshlrev_b32_e32 v104, 6, v104
	s_and_saveexec_b64 s[100:101], s[98:99]
	s_cbranch_execz .Lpwt_0_a
	v_add_u32_e32 v138, v111, v105
	v_add_u32_e32 v139, v138, v7
	v_and_b32_e32 v138, 0xffffff80, v138
	v_and_b32_e32 v140, 0x4c, v139
	s_movk_i32 s0, 0xa00
	v_or3_b32 v138, v10, v138, v140
	v_cmp_gt_i32_e64 s[0:1], s0, v139
	v_or_b32_e32 v150, v104, v6
	v_or_b32_e32 v140, 16, v150
	v_cndmask_b32_e64 v138, v139, v138, s[0:1]
	v_ashrrev_i32_e32 v139, 31, v138
	v_lshl_add_u64 v[146:147], v[138:139], 2, s[4:5]
	v_mad_i64_i32 v[138:139], s[0:1], v150, s59, v[146:147]
	v_or_b32_e32 v148, 32, v150
	v_or_b32_e32 v150, 48, v150
	v_mad_i64_i32 v[142:143], s[0:1], v140, s59, v[146:147]
	v_mad_i64_i32 v[148:149], s[0:1], v148, s59, v[146:147]
	v_mad_i64_i32 v[150:151], s[0:1], v150, s59, v[146:147]
	v_mov_b32_e32 v160, v138
	v_mov_b32_e32 v161, v139
	global_load_dwordx4 v[138:141], v[138:139], off
	s_nop 0
	global_load_dwordx4 v[142:145], v[142:143], off
	s_nop 0
	global_load_dwordx4 v[146:149], v[148:149], off
	s_nop 0
	global_load_dwordx4 v[150:153], v[150:151], off
	global_load_dword v162, v[160:161], off
.Lpwt_0_a:
	s_or_b64 exec, exec, s[100:101]
	s_branch .LBB0_30

.LBB0_30:
	v_mul_hi_i32 v4, v9, s58
	s_movk_i32 s0, 0x600
	v_lshrrev_b32_e32 v5, 31, v4
	v_ashrrev_i32_e32 v4, 3, v4
	v_cmp_gt_i32_e32 vcc, s0, v9
	v_add_u32_e32 v4, v4, v5
	s_movk_i32 s0, 0xf400
	v_mul_lo_u32 v5, v4, s0
	v_lshlrev_b32_e32 v4, 6, v4
	s_and_saveexec_b64 s[8:9], vcc
	s_cbranch_execz .LBB0_32
	s_waitcnt vmcnt(1)
	ds_write_b128 v12, v[138:141]
	ds_write_b128 v13, v[142:145]
	ds_write_b128 v14, v[146:149]
	ds_write_b128 v15, v[150:153]
	v_add_u32_e32 v109, s3, v9
	v_add_u32_e32 v111, s10, v11
	v_mul_hi_i32 v104, v109, s58
	s_movk_i32 s0, 0x600
	v_lshrrev_b32_e32 v105, 31, v104
	v_ashrrev_i32_e32 v104, 3, v104
	v_cmp_gt_i32_e64 s[98:99], s0, v109
	v_add_u32_e32 v104, v104, v105
	s_movk_i32 s0, 0xf400
	v_mul_lo_u32 v105, v104, s0
	v_lshlrev_b32_e32 v104, 6, v104
	s_and_saveexec_b64 s[100:101], s[98:99]
	s_cbranch_execz .Lpwt_0_b
	v_add_u32_e32 v138, v111, v105
	v_add_u32_e32 v139, v138, v7
	v_and_b32_e32 v138, 0xffffff80, v138
	v_and_b32_e32 v140, 0x4c, v139
	s_movk_i32 s0, 0xa00
	v_or3_b32 v138, v10, v138, v140
	v_cmp_gt_i32_e64 s[0:1], s0, v139
	v_or_b32_e32 v150, v104, v6
	v_or_b32_e32 v140, 16, v150
	v_cndmask_b32_e64 v138, v139, v138, s[0:1]
	v_ashrrev_i32_e32 v139, 31, v138
	v_lshl_add_u64 v[146:147], v[138:139], 2, s[4:5]
	v_mad_i64_i32 v[138:139], s[0:1], v150, s59, v[146:147]
	v_or_b32_e32 v148, 32, v150
	v_or_b32_e32 v150, 48, v150
	v_mad_i64_i32 v[142:143], s[0:1], v140, s59, v[146:147]
	v_mad_i64_i32 v[148:149], s[0:1], v148, s59, v[146:147]
	v_mad_i64_i32 v[150:151], s[0:1], v150, s59, v[146:147]
	global_load_dwordx4 v[138:141], v[138:139], off
	s_nop 0
	global_load_dwordx4 v[142:145], v[142:143], off
	s_nop 0
	global_load_dwordx4 v[146:149], v[148:149], off
	s_nop 0
	global_load_dwordx4 v[150:153], v[150:151], off
.Lpwt_0_b:
	s_or_b64 exec, exec, s[100:101]

.LBB0_34:
	v_mov_b32_e32 v4, v0
	s_lshl_b64 s[4:5], s[26:27], 22
	s_mov_b64 s[0:1], 0
	v_cmp_ne_u32_e64 s[72:73], 1, v1
	s_andn2_b64 vcc, exec, s[24:25]
	s_cbranch_vccnz .LBB0_41
	v_readlane_b32 s8, v250, 41
	s_lshl_b64 s[6:7], s[4:5], 2
	v_readlane_b32 s9, v250, 42
	v_readlane_b32 s10, v250, 43
	v_readlane_b32 s11, v250, 44
	v_readlane_b32 s12, v250, 45
	v_readlane_b32 s13, v250, 46
	s_add_u32 s6, s12, s6
	v_readlane_b32 s8, v250, 0
	s_addc_u32 s7, s13, s7
	v_readlane_b32 s10, v250, 2
	v_readlane_b32 s11, v250, 3
	s_add_u32 s0, s10, s0
	s_addc_u32 s1, s11, s1
	s_add_u32 s0, s0, s4
	s_addc_u32 s1, s1, s5
	v_lshlrev_b32_e32 v2, 2, v4
	s_add_u32 s10, s0, 0x2d7e6000
	v_and_b32_e32 v7, 60, v2
	v_ashrrev_i32_e32 v2, 8, v4
	v_readlane_b32 s0, v250, 27
	v_lshl_add_u32 v9, v2, 16, 0
	v_lshlrev_b32_e32 v5, 1, v4
	v_add_u32_e32 v10, s0, v2
	v_lshlrev_b32_e32 v2, 4, v4
	v_and_b32_e32 v2, 48, v2
	v_bfe_u32 v6, v4, 4, 4
	v_bfe_u32 v8, v4, 2, 6
	v_and_b32_e32 v5, 16, v5
	v_lshlrev_b32_e32 v4, 3, v4
	v_mul_u32_u24_e32 v13, 0x44, v2
	v_and_or_b32 v11, v4, 32, v5
	v_mul_u32_u24_e32 v4, 0x44, v6
	v_or_b32_e32 v13, v13, v8
	v_add_lshl_u32 v12, v4, v7, 2
	v_lshlrev_b32_e32 v13, 2, v13
	v_readlane_b32 s15, v250, 48
	v_readlane_b32 s16, v250, 49
	v_add_u32_e32 v4, 0x1100, v12
	v_add_u32_e32 v5, 0x2200, v12
	v_add_u32_e32 v17, 0x3300, v12
	v_add_u32_e32 v18, 0x110, v13
	v_add_u32_e32 v19, 0x220, v13
	v_add_u32_e32 v26, 0x330, v13
	v_add_u32_e32 v27, 0x440, v13
	v_add_u32_e32 v28, 0x550, v13
	v_add_u32_e32 v29, 0x660, v13
	v_add_u32_e32 v30, 0x770, v13
	v_add_u32_e32 v31, 0x880, v13
	v_add_u32_e32 v32, 0x990, v13
	v_add_u32_e32 v33, 0xaa0, v13
	v_add_u32_e32 v34, 0xbb0, v13
	v_add_u32_e32 v35, 0xcc0, v13
	v_add_u32_e32 v36, 0xdd0, v13
	v_add_u32_e32 v37, 0xee0, v13
	v_add_u32_e32 v38, 0xff0, v13
	s_addc_u32 s11, s1, 0
	v_lshlrev_b32_e32 v14, 6, v10
	s_lshl_b32 s15, s3, 6
	v_add_u32_e32 v15, v9, v4
	v_add_u32_e32 v16, v9, v5
	v_add_u32_e32 v17, v9, v17
	v_add_u32_e32 v18, v9, v18
	v_add_u32_e32 v19, v9, v19
	v_add_u32_e32 v26, v9, v26
	v_add_u32_e32 v27, v9, v27
	v_add_u32_e32 v28, v9, v28
	v_add_u32_e32 v29, v9, v29
	v_add_u32_e32 v30, v9, v30
	v_add_u32_e32 v31, v9, v31
	v_add_u32_e32 v32, v9, v32
	v_add_u32_e32 v33, v9, v33
	v_add_u32_e32 v34, v9, v34
	v_add_u32_e32 v35, v9, v35
	v_add_u32_e32 v36, v9, v36
	v_add_u32_e32 v37, v9, v37
	v_add_u32_e32 v38, v9, v38
	s_mov_b32 s16, s77
	v_readlane_b32 s14, v250, 47
	v_readlane_b32 s17, v250, 50
	v_readlane_b32 s18, v250, 51
	v_readlane_b32 s19, v250, 52
	v_readlane_b32 s20, v250, 53
	v_readlane_b32 s21, v250, 54
	v_readlane_b32 s22, v250, 55
	v_readlane_b32 s23, v250, 56
	v_readlane_b32 s9, v250, 1
	v_mov_b32_e32 v110, v10
	v_mov_b32_e32 v114, v14
	v_ashrrev_i32_e32 v104, 31, v110
	v_lshrrev_b32_e32 v104, 27, v104
	v_add_u32_e32 v104, v110, v104
	v_ashrrev_i32_e32 v139, 5, v104
	v_lshlrev_b32_e32 v104, 11, v139
	v_cmp_gt_i32_e64 s[98:99], s61, v110
	v_sub_u32_e32 v105, 0, v104
	v_lshlrev_b32_e32 v104, 6, v139
	s_and_saveexec_b64 s[100:101], s[98:99]
	s_cbranch_execz .Lpwt_1_a
	v_add_u32_e32 v140, v114, v105
	v_lshlrev_b32_e32 v139, 5, v139
	v_add_u32_e32 v141, v140, v7
	v_sub_u32_e32 v139, v110, v139
	v_and_b32_e32 v140, 0xffffff80, v140
	v_and_b32_e32 v142, 0x4c, v141
	v_or3_b32 v140, v11, v140, v142
	v_cmp_gt_i32_e64 s[0:1], 0, v139
	v_or_b32_e32 v148, v104, v6
	v_ashrrev_i32_e32 v149, 31, v148
	v_cndmask_b32_e64 v140, v141, v140, s[0:1]
	v_ashrrev_i32_e32 v141, 31, v140
	v_lshl_add_u64 v[150:151], v[140:141], 2, s[6:7]
	v_lshlrev_b64 v[140:141], 13, v[148:149]
	v_or_b32_e32 v142, 16, v148
	v_or_b32_e32 v152, 32, v148
	v_or_b32_e32 v148, 48, v148
	v_ashrrev_i32_e32 v143, 31, v142
	v_ashrrev_i32_e32 v153, 31, v152
	v_ashrrev_i32_e32 v149, 31, v148
	v_lshlrev_b64 v[142:143], 13, v[142:143]
	v_lshlrev_b64 v[152:153], 13, v[152:153]
	v_lshlrev_b64 v[148:149], 13, v[148:149]
	v_lshl_add_u64 v[140:141], v[150:151], 0, v[140:141]
	v_lshl_add_u64 v[144:145], v[150:151], 0, v[142:143]
	v_lshl_add_u64 v[152:153], v[150:151], 0, v[152:153]
	v_lshl_add_u64 v[154:155], v[150:151], 0, v[148:149]
	v_mov_b32_e32 v160, v140
	v_mov_b32_e32 v161, v141
	global_load_dwordx4 v[140:143], v[140:141], off
	s_nop 0
	global_load_dwordx4 v[144:147], v[144:145], off
	s_nop 0
	global_load_dwordx4 v[148:151], v[152:153], off
	s_nop 0
	global_load_dwordx4 v[152:155], v[154:155], off
	global_load_dword v162, v[160:161], off

.LBB0_37:
	v_ashrrev_i32_e32 v4, 31, v10
	v_lshrrev_b32_e32 v4, 27, v4
	v_add_u32_e32 v4, v10, v4
	v_ashrrev_i32_e32 v39, 5, v4
	v_lshlrev_b32_e32 v4, 11, v39
	v_cmp_gt_i32_e32 vcc, s61, v10
	v_sub_u32_e32 v5, 0, v4
	v_lshlrev_b32_e32 v4, 6, v39
	s_and_saveexec_b64 s[12:13], vcc
	s_cbranch_execz .LBB0_39
	s_waitcnt vmcnt(1)
	v_add_u32_e32 v39, v9, v12
	ds_write_b128 v39, v[140:143]
	ds_write_b128 v15, v[144:147]
	ds_write_b128 v16, v[148:151]
	ds_write_b128 v17, v[152:155]
	v_add_u32_e32 v110, s3, v10
	v_add_u32_e32 v114, s15, v14
	v_ashrrev_i32_e32 v104, 31, v110
	v_lshrrev_b32_e32 v104, 27, v104
	v_add_u32_e32 v104, v110, v104
	v_ashrrev_i32_e32 v139, 5, v104
	v_lshlrev_b32_e32 v104, 11, v139
	v_cmp_gt_i32_e64 s[98:99], s61, v110
	v_sub_u32_e32 v105, 0, v104
	v_lshlrev_b32_e32 v104, 6, v139
	s_and_saveexec_b64 s[100:101], s[98:99]
	s_cbranch_execz .Lpwt_1_b
	v_add_u32_e32 v140, v114, v105
	v_lshlrev_b32_e32 v139, 5, v139
	v_add_u32_e32 v141, v140, v7
	v_sub_u32_e32 v139, v110, v139
	v_and_b32_e32 v140, 0xffffff80, v140
	v_and_b32_e32 v142, 0x4c, v141
	v_or3_b32 v140, v11, v140, v142
	v_cmp_gt_i32_e64 s[0:1], 0, v139
	v_or_b32_e32 v148, v104, v6
	v_ashrrev_i32_e32 v149, 31, v148
	v_cndmask_b32_e64 v140, v141, v140, s[0:1]
	v_ashrrev_i32_e32 v141, 31, v140
	v_lshl_add_u64 v[150:151], v[140:141], 2, s[6:7]
	v_lshlrev_b64 v[140:141], 13, v[148:149]
	v_or_b32_e32 v142, 16, v148
	v_or_b32_e32 v152, 32, v148
	v_or_b32_e32 v148, 48, v148
	v_ashrrev_i32_e32 v143, 31, v142
	v_ashrrev_i32_e32 v153, 31, v152
	v_ashrrev_i32_e32 v149, 31, v148
	v_lshlrev_b64 v[142:143], 13, v[142:143]
	v_lshlrev_b64 v[152:153], 13, v[152:153]
	v_lshlrev_b64 v[148:149], 13, v[148:149]
	v_lshl_add_u64 v[140:141], v[150:151], 0, v[140:141]
	v_lshl_add_u64 v[144:145], v[150:151], 0, v[142:143]
	v_lshl_add_u64 v[152:153], v[150:151], 0, v[152:153]
	v_lshl_add_u64 v[154:155], v[150:151], 0, v[148:149]
	global_load_dwordx4 v[140:143], v[140:141], off
	s_nop 0
	global_load_dwordx4 v[144:147], v[144:145], off
	s_nop 0
	global_load_dwordx4 v[148:151], v[152:153], off
	s_nop 0
	global_load_dwordx4 v[152:155], v[154:155], off

.LBB0_41:
	v_readlane_b32 s6, v250, 37
	v_readlane_b32 s7, v250, 38
	v_mov_b32_e32 v2, v0
	s_mov_b64 s[0:1], 0
	s_andn2_b64 vcc, exec, s[6:7]
	s_cbranch_vccnz .LBB0_48
	v_readlane_b32 s8, v250, 41
	s_mul_i32 s6, s26, 0x3000000
	v_readlane_b32 s9, v250, 42
	v_readlane_b32 s10, v250, 43
	v_readlane_b32 s11, v250, 44
	v_readlane_b32 s16, v250, 49
	v_readlane_b32 s17, v250, 50
	s_add_u32 s6, s16, s6
	v_readlane_b32 s8, v250, 0
	s_addc_u32 s7, s17, 0
	v_readlane_b32 s10, v250, 2
	v_readlane_b32 s11, v250, 3
	s_add_u32 s0, s10, s0
	v_lshlrev_b32_e32 v6, 4, v2
	s_addc_u32 s1, s11, s1
	v_lshlrev_b32_e32 v4, 2, v2
	v_and_b32_e32 v6, 48, v6
	v_lshlrev_b32_e32 v7, 1, v2
	s_add_u32 s0, s0, s84
	v_bfe_u32 v5, v2, 4, 4
	v_and_b32_e32 v8, 60, v4
	v_bfe_u32 v9, v2, 2, 6
	v_ashrrev_i32_e32 v4, 8, v2
	v_and_b32_e32 v7, 16, v7
	v_lshlrev_b32_e32 v2, 3, v2
	v_mul_u32_u24_e32 v13, 0x44, v6
	s_addc_u32 s1, s1, 0
	v_and_or_b32 v11, v2, 32, v7
	v_mul_u32_u24_e32 v2, 0x44, v5
	v_or_b32_e32 v13, v13, v9
	s_add_u32 s10, s0, 0x2e7e6000
	v_readlane_b32 s0, v250, 27
	v_add_lshl_u32 v12, v2, v8, 2
	v_lshlrev_b32_e32 v13, 2, v13
	v_readlane_b32 s14, v250, 47
	v_readlane_b32 s15, v250, 48
	v_lshl_add_u32 v10, v4, 16, 0
	v_add_u32_e32 v4, s0, v4
	v_add_u32_e32 v2, 0x1100, v12
	v_add_u32_e32 v7, 0x2200, v12
	v_add_u32_e32 v17, 0x3300, v12
	v_add_u32_e32 v18, 0x110, v13
	v_add_u32_e32 v19, 0x220, v13
	v_add_u32_e32 v26, 0x330, v13
	v_add_u32_e32 v27, 0x440, v13
	v_add_u32_e32 v28, 0x550, v13
	v_add_u32_e32 v29, 0x660, v13
	v_add_u32_e32 v30, 0x770, v13
	v_add_u32_e32 v31, 0x880, v13
	v_add_u32_e32 v32, 0x990, v13
	v_add_u32_e32 v33, 0xaa0, v13
	v_add_u32_e32 v34, 0xbb0, v13
	v_add_u32_e32 v35, 0xcc0, v13
	v_add_u32_e32 v36, 0xdd0, v13
	v_add_u32_e32 v37, 0xee0, v13
	v_add_u32_e32 v38, 0xff0, v13
	s_addc_u32 s11, s1, 0
	v_lshlrev_b32_e32 v14, 6, v4
	s_lshl_b32 s14, s3, 6
	v_add_u32_e32 v15, v10, v2
	v_add_u32_e32 v16, v10, v7
	v_add_u32_e32 v17, v10, v17
	v_add_u32_e32 v18, v10, v18
	v_add_u32_e32 v19, v10, v19
	v_add_u32_e32 v26, v10, v26
	v_add_u32_e32 v27, v10, v27
	v_add_u32_e32 v28, v10, v28
	v_add_u32_e32 v29, v10, v29
	v_add_u32_e32 v30, v10, v30
	v_add_u32_e32 v31, v10, v31
	v_add_u32_e32 v32, v10, v32
	v_add_u32_e32 v33, v10, v33
	v_add_u32_e32 v34, v10, v34
	v_add_u32_e32 v35, v10, v35
	v_add_u32_e32 v36, v10, v36
	v_add_u32_e32 v37, v10, v37
	v_add_u32_e32 v38, v10, v38
	v_lshlrev_b32_e32 v2, 1, v6
	v_readlane_b32 s15, v250, 35
	v_readlane_b32 s12, v250, 45
	v_readlane_b32 s13, v250, 46
	v_readlane_b32 s18, v250, 51
	v_readlane_b32 s19, v250, 52
	v_readlane_b32 s20, v250, 53
	v_readlane_b32 s21, v250, 54
	v_readlane_b32 s22, v250, 55
	v_readlane_b32 s23, v250, 56
	v_readlane_b32 s9, v250, 1
	v_mov_b32_e32 v104, v4
	v_mov_b32_e32 v114, v14
	v_mov_b32_e32 v105, v5
	v_mul_hi_i32 v106, v104, s58
	s_movk_i32 s0, 0xc00
	v_lshrrev_b32_e32 v107, 31, v106
	v_ashrrev_i32_e32 v106, 4, v106
	v_cmp_gt_i32_e64 s[98:99], s0, v104
	v_add_u32_e32 v139, v106, v107
	s_movk_i32 s0, 0xe800
	v_mul_lo_u32 v107, v139, s0
	v_lshlrev_b32_e32 v106, 6, v139
	s_and_saveexec_b64 s[100:101], s[98:99]
	s_cbranch_execz .Lpwt_2_a
	s_movk_i32 s0, 0xffa0
	v_mad_u64_u32 v[140:141], s[0:1], v139, s0, v[104:105]
	v_add_u32_e32 v139, v114, v107
	v_add_u32_e32 v141, v139, v8
	v_and_b32_e32 v139, 0xffffff80, v139
	v_and_b32_e32 v142, 0x4c, v141
	v_or3_b32 v139, v11, v139, v142
	v_cmp_gt_i32_e64 s[0:1], 0, v140
	s_nop 1
	v_cndmask_b32_e64 v140, v141, v139, s[0:1]
	v_ashrrev_i32_e32 v141, 31, v140
	v_or_b32_e32 v139, v106, v105
	v_lshl_add_u64 v[148:149], v[140:141], 2, s[6:7]
	v_mad_i64_i32 v[140:141], s[0:1], v139, s62, v[148:149]
	v_or_b32_e32 v142, 16, v139
	v_or_b32_e32 v150, 32, v139
	v_or_b32_e32 v139, 48, v139
	v_mad_i64_i32 v[144:145], s[0:1], v142, s62, v[148:149]
	v_mad_i64_i32 v[150:151], s[0:1], v150, s62, v[148:149]
	v_mad_i64_i32 v[152:153], s[0:1], v139, s62, v[148:149]
	v_mov_b32_e32 v160, v140
	v_mov_b32_e32 v161, v141
	global_load_dwordx4 v[140:143], v[140:141], off
	s_nop 0
	global_load_dwordx4 v[144:147], v[144:145], off
	s_nop 0
	global_load_dwordx4 v[148:151], v[150:151], off
	s_nop 0
	global_load_dwordx4 v[152:155], v[152:153], off
	global_load_dword v162, v[160:161], off
	global_load_dword v162, v[160:161], off

.LBB0_44:
	v_mul_hi_i32 v6, v4, s58
	s_movk_i32 s0, 0xc00
	v_lshrrev_b32_e32 v7, 31, v6
	v_ashrrev_i32_e32 v6, 4, v6
	v_cmp_gt_i32_e32 vcc, s0, v4
	v_add_u32_e32 v39, v6, v7
	s_movk_i32 s0, 0xe800
	v_mul_lo_u32 v7, v39, s0
	v_lshlrev_b32_e32 v6, 6, v39
	s_and_saveexec_b64 s[12:13], vcc
	s_cbranch_execz .LBB0_46
	s_waitcnt vmcnt(2)
	v_add_u32_e32 v39, v10, v12
	ds_write_b128 v39, v[140:143]
	ds_write_b128 v15, v[144:147]
	ds_write_b128 v16, v[148:151]
	ds_write_b128 v17, v[152:155]
	v_add_u32_e32 v104, s3, v4
	v_add_u32_e32 v114, s14, v14
	v_mov_b32_e32 v105, v5
	v_mul_hi_i32 v106, v104, s58
	s_movk_i32 s0, 0xc00
	v_lshrrev_b32_e32 v107, 31, v106
	v_ashrrev_i32_e32 v106, 4, v106
	v_cmp_gt_i32_e64 s[98:99], s0, v104
	v_add_u32_e32 v139, v106, v107
	s_movk_i32 s0, 0xe800
	v_mul_lo_u32 v107, v139, s0
	v_lshlrev_b32_e32 v106, 6, v139
	s_and_saveexec_b64 s[100:101], s[98:99]
	s_cbranch_execz .Lpwt_2_b
	s_movk_i32 s0, 0xffa0
	v_mad_u64_u32 v[140:141], s[0:1], v139, s0, v[104:105]
	v_add_u32_e32 v139, v114, v107
	v_add_u32_e32 v141, v139, v8
	v_and_b32_e32 v139, 0xffffff80, v139
	v_and_b32_e32 v142, 0x4c, v141
	v_or3_b32 v139, v11, v139, v142
	v_cmp_gt_i32_e64 s[0:1], 0, v140
	s_nop 1
	v_cndmask_b32_e64 v140, v141, v139, s[0:1]
	v_ashrrev_i32_e32 v141, 31, v140
	v_or_b32_e32 v139, v106, v105
	v_lshl_add_u64 v[148:149], v[140:141], 2, s[6:7]
	v_mad_i64_i32 v[140:141], s[0:1], v139, s62, v[148:149]
	v_or_b32_e32 v142, 16, v139
	v_or_b32_e32 v150, 32, v139
	v_or_b32_e32 v139, 48, v139
	v_mad_i64_i32 v[144:145], s[0:1], v142, s62, v[148:149]
	v_mad_i64_i32 v[150:151], s[0:1], v150, s62, v[148:149]
	v_mad_i64_i32 v[152:153], s[0:1], v139, s62, v[148:149]
	global_load_dwordx4 v[140:143], v[140:141], off
	s_nop 0
	global_load_dwordx4 v[144:147], v[144:145], off
	s_nop 0
	global_load_dwordx4 v[148:151], v[150:151], off
	s_nop 0
	global_load_dwordx4 v[152:155], v[152:153], off

.LBB0_48:
	v_mov_b32_e32 v2, v0
	s_mov_b64 s[0:1], 0
	s_and_b64 vcc, exec, s[72:73]
	s_cbranch_vccnz .LBB0_55
	s_lshl_b64 s[6:7], s[4:5], 2
	s_add_u32 s6, s48, s6
	v_readlane_b32 s8, v250, 0
	s_addc_u32 s7, s49, s7
	v_readlane_b32 s10, v250, 2
	v_readlane_b32 s11, v250, 3
	s_add_u32 s10, s10, s0
	s_addc_u32 s11, s11, s1
	s_lshl_b64 s[0:1], s[4:5], 1
	s_add_u32 s0, s10, s0
	s_addc_u32 s1, s11, s1
	v_lshlrev_b32_e32 v4, 2, v2
	s_add_u32 s4, s0, 0x317e6000
	v_and_b32_e32 v7, 60, v4
	v_ashrrev_i32_e32 v4, 8, v2
	v_readlane_b32 s0, v250, 27
	v_lshl_add_u32 v9, v4, 16, 0
	v_lshlrev_b32_e32 v5, 1, v2
	v_add_u32_e32 v10, s0, v4
	v_lshlrev_b32_e32 v4, 4, v2
	v_and_b32_e32 v4, 48, v4
	v_bfe_u32 v6, v2, 4, 4
	v_bfe_u32 v8, v2, 2, 6
	v_and_b32_e32 v5, 16, v5
	v_lshlrev_b32_e32 v2, 3, v2
	v_mul_u32_u24_e32 v13, 0x44, v4
	v_and_or_b32 v11, v2, 32, v5
	v_mul_u32_u24_e32 v2, 0x44, v6
	v_or_b32_e32 v13, v13, v8
	v_add_lshl_u32 v12, v2, v7, 2
	v_lshlrev_b32_e32 v13, 2, v13
	v_add_u32_e32 v2, 0x1100, v12
	v_add_u32_e32 v5, 0x2200, v12
	v_add_u32_e32 v17, 0x3300, v12
	v_add_u32_e32 v18, 0x110, v13
	v_add_u32_e32 v19, 0x220, v13
	v_add_u32_e32 v26, 0x330, v13
	v_add_u32_e32 v27, 0x440, v13
	v_add_u32_e32 v28, 0x550, v13
	v_add_u32_e32 v29, 0x660, v13
	v_add_u32_e32 v30, 0x770, v13
	v_add_u32_e32 v31, 0x880, v13
	v_add_u32_e32 v32, 0x990, v13
	v_add_u32_e32 v33, 0xaa0, v13
	v_add_u32_e32 v34, 0xbb0, v13
	v_add_u32_e32 v35, 0xcc0, v13
	v_add_u32_e32 v36, 0xdd0, v13
	v_add_u32_e32 v37, 0xee0, v13
	v_add_u32_e32 v38, 0xff0, v13
	s_addc_u32 s5, s1, 0
	v_lshlrev_b32_e32 v14, 6, v10
	s_lshl_b32 s12, s3, 6
	v_add_u32_e32 v15, v9, v2
	v_add_u32_e32 v16, v9, v5
	v_add_u32_e32 v17, v9, v17
	v_add_u32_e32 v18, v9, v18
	v_add_u32_e32 v19, v9, v19
	v_add_u32_e32 v26, v9, v26
	v_add_u32_e32 v27, v9, v27
	v_add_u32_e32 v28, v9, v28
	v_add_u32_e32 v29, v9, v29
	v_add_u32_e32 v30, v9, v30
	v_add_u32_e32 v31, v9, v31
	v_add_u32_e32 v32, v9, v32
	v_add_u32_e32 v33, v9, v33
	v_add_u32_e32 v34, v9, v34
	v_add_u32_e32 v35, v9, v35
	v_add_u32_e32 v36, v9, v36
	v_add_u32_e32 v37, v9, v37
	v_add_u32_e32 v38, v9, v38
	v_lshlrev_b32_e32 v2, 1, v4
	s_mov_b32 s13, s77
	v_readlane_b32 s9, v250, 1
	v_mov_b32_e32 v110, v10
	v_mov_b32_e32 v114, v14
	v_ashrrev_i32_e32 v104, 31, v110
	v_lshrrev_b32_e32 v104, 27, v104
	v_add_u32_e32 v104, v110, v104
	v_ashrrev_i32_e32 v139, 5, v104
	v_lshlrev_b32_e32 v104, 11, v139
	v_cmp_gt_i32_e64 s[98:99], s61, v110
	v_sub_u32_e32 v105, 0, v104
	v_lshlrev_b32_e32 v104, 6, v139
	s_and_saveexec_b64 s[100:101], s[98:99]
	s_cbranch_execz .Lpwt_3_a
	v_add_u32_e32 v140, v114, v105
	v_lshlrev_b32_e32 v139, 5, v139
	v_add_u32_e32 v141, v140, v7
	v_sub_u32_e32 v139, v110, v139
	v_and_b32_e32 v140, 0xffffff80, v140
	v_and_b32_e32 v142, 0x4c, v141
	v_or3_b32 v140, v11, v140, v142
	v_cmp_gt_i32_e64 s[0:1], 0, v139
	v_or_b32_e32 v148, v104, v6
	v_ashrrev_i32_e32 v149, 31, v148
	v_cndmask_b32_e64 v140, v141, v140, s[0:1]
	v_ashrrev_i32_e32 v141, 31, v140
	v_lshl_add_u64 v[150:151], v[140:141], 2, s[6:7]
	v_lshlrev_b64 v[140:141], 13, v[148:149]
	v_or_b32_e32 v142, 16, v148
	v_or_b32_e32 v152, 32, v148
	v_or_b32_e32 v148, 48, v148
	v_ashrrev_i32_e32 v143, 31, v142
	v_ashrrev_i32_e32 v153, 31, v152
	v_ashrrev_i32_e32 v149, 31, v148
	v_lshlrev_b64 v[142:143], 13, v[142:143]
	v_lshlrev_b64 v[152:153], 13, v[152:153]
	v_lshlrev_b64 v[148:149], 13, v[148:149]
	v_lshl_add_u64 v[140:141], v[150:151], 0, v[140:141]
	v_lshl_add_u64 v[144:145], v[150:151], 0, v[142:143]
	v_lshl_add_u64 v[152:153], v[150:151], 0, v[152:153]
	v_lshl_add_u64 v[154:155], v[150:151], 0, v[148:149]
	v_mov_b32_e32 v160, v140
	v_mov_b32_e32 v161, v141
	global_load_dwordx4 v[140:143], v[140:141], off
	s_nop 0
	global_load_dwordx4 v[144:147], v[144:145], off
	s_nop 0
	global_load_dwordx4 v[148:151], v[152:153], off
	s_nop 0
	global_load_dwordx4 v[152:155], v[154:155], off
	global_load_dword v162, v[160:161], off
	global_load_dword v162, v[160:161], off

.LBB0_51:
	v_ashrrev_i32_e32 v4, 31, v10
	v_lshrrev_b32_e32 v4, 27, v4
	v_add_u32_e32 v4, v10, v4
	v_ashrrev_i32_e32 v39, 5, v4
	v_lshlrev_b32_e32 v4, 11, v39
	v_cmp_gt_i32_e32 vcc, s61, v10
	v_sub_u32_e32 v5, 0, v4
	v_lshlrev_b32_e32 v4, 6, v39
	s_and_saveexec_b64 s[10:11], vcc
	s_cbranch_execz .LBB0_53
	s_waitcnt vmcnt(2)
	v_add_u32_e32 v39, v9, v12
	ds_write_b128 v39, v[140:143]
	ds_write_b128 v15, v[144:147]
	ds_write_b128 v16, v[148:151]
	ds_write_b128 v17, v[152:155]
	v_add_u32_e32 v110, s3, v10
	v_add_u32_e32 v114, s12, v14
	v_ashrrev_i32_e32 v104, 31, v110
	v_lshrrev_b32_e32 v104, 27, v104
	v_add_u32_e32 v104, v110, v104
	v_ashrrev_i32_e32 v139, 5, v104
	v_lshlrev_b32_e32 v104, 11, v139
	v_cmp_gt_i32_e64 s[98:99], s61, v110
	v_sub_u32_e32 v105, 0, v104
	v_lshlrev_b32_e32 v104, 6, v139
	s_and_saveexec_b64 s[100:101], s[98:99]
	s_cbranch_execz .Lpwt_3_b
	v_add_u32_e32 v140, v114, v105
	v_lshlrev_b32_e32 v139, 5, v139
	v_add_u32_e32 v141, v140, v7
	v_sub_u32_e32 v139, v110, v139
	v_and_b32_e32 v140, 0xffffff80, v140
	v_and_b32_e32 v142, 0x4c, v141
	v_or3_b32 v140, v11, v140, v142
	v_cmp_gt_i32_e64 s[0:1], 0, v139
	v_or_b32_e32 v148, v104, v6
	v_ashrrev_i32_e32 v149, 31, v148
	v_cndmask_b32_e64 v140, v141, v140, s[0:1]
	v_ashrrev_i32_e32 v141, 31, v140
	v_lshl_add_u64 v[150:151], v[140:141], 2, s[6:7]
	v_lshlrev_b64 v[140:141], 13, v[148:149]
	v_or_b32_e32 v142, 16, v148
	v_or_b32_e32 v152, 32, v148
	v_or_b32_e32 v148, 48, v148
	v_ashrrev_i32_e32 v143, 31, v142
	v_ashrrev_i32_e32 v153, 31, v152
	v_ashrrev_i32_e32 v149, 31, v148
	v_lshlrev_b64 v[142:143], 13, v[142:143]
	v_lshlrev_b64 v[152:153], 13, v[152:153]
	v_lshlrev_b64 v[148:149], 13, v[148:149]
	v_lshl_add_u64 v[140:141], v[150:151], 0, v[140:141]
	v_lshl_add_u64 v[144:145], v[150:151], 0, v[142:143]
	v_lshl_add_u64 v[152:153], v[150:151], 0, v[152:153]
	v_lshl_add_u64 v[154:155], v[150:151], 0, v[148:149]
	global_load_dwordx4 v[140:143], v[140:141], off
	s_nop 0
	global_load_dwordx4 v[144:147], v[144:145], off
	s_nop 0
	global_load_dwordx4 v[148:151], v[152:153], off
	s_nop 0
	global_load_dwordx4 v[152:155], v[154:155], off

.LBB0_137:
	v_readlane_b32 s78, v250, 22
	v_mov_b32_e32 v3, v0
	s_mov_b64 s[4:5], 0
	s_mov_b64 s[0:1], 0
	s_and_b64 vcc, exec, s[24:25]
	v_readlane_b32 s74, v250, 24
	v_readlane_b32 s79, v250, 23
	s_cbranch_vccz .LBB0_144
	v_readlane_b32 s8, v250, 0
	v_readlane_b32 s10, v250, 2
	v_readlane_b32 s11, v250, 3
	s_add_u32 s0, s10, s0
	s_addc_u32 s1, s11, s1
	v_lshlrev_b32_e32 v2, 2, v3
	s_add_u32 s6, s0, 0x327e6000
	v_and_b32_e32 v6, 60, v2
	v_ashrrev_i32_e32 v2, 8, v3
	v_readlane_b32 s0, v250, 27
	v_lshl_add_u32 v4, v2, 16, 0
	v_lshlrev_b32_e32 v5, 1, v3
	v_add_u32_e32 v8, s0, v2
	v_lshlrev_b32_e32 v2, 4, v3
	v_and_b32_e32 v2, 48, v2
	v_bfe_u32 v1, v3, 4, 4
	v_bfe_u32 v7, v3, 2, 6
	v_and_b32_e32 v5, 16, v5
	v_lshlrev_b32_e32 v3, 3, v3
	v_mul_u32_u24_e32 v10, 0x44, v2
	v_and_or_b32 v9, v3, 32, v5
	v_mul_u32_u24_e32 v5, 0x44, v1
	v_or_b32_e32 v10, v10, v7
	v_add_lshl_u32 v5, v5, v6, 2
	v_lshlrev_b32_e32 v15, 2, v10
	v_add_u32_e32 v12, 0x1100, v5
	v_add_u32_e32 v13, 0x2200, v5
	v_add_u32_e32 v14, 0x3300, v5
	v_add_u32_e32 v16, 0x110, v15
	v_add_u32_e32 v17, 0x220, v15
	v_add_u32_e32 v18, 0x330, v15
	v_add_u32_e32 v19, 0x440, v15
	v_add_u32_e32 v20, 0x550, v15
	v_add_u32_e32 v21, 0x660, v15
	v_add_u32_e32 v22, 0x770, v15
	v_add_u32_e32 v23, 0x880, v15
	v_add_u32_e32 v24, 0x990, v15
	v_add_u32_e32 v25, 0xaa0, v15
	v_add_u32_e32 v26, 0xbb0, v15
	v_add_u32_e32 v27, 0xcc0, v15
	v_add_u32_e32 v28, 0xdd0, v15
	v_add_u32_e32 v29, 0xee0, v15
	v_add_u32_e32 v30, 0xff0, v15
	s_addc_u32 s7, s1, 0
	v_mov_b32_e32 v3, 0
	v_lshlrev_b32_e32 v10, 6, v8
	s_lshl_b32 s2, s3, 6
	s_movk_i32 s12, 0x400
	v_add_u32_e32 v11, v4, v5
	v_add_u32_e32 v12, v4, v12
	v_add_u32_e32 v13, v4, v13
	v_add_u32_e32 v14, v4, v14
	v_add_u32_e32 v15, v4, v15
	v_add_u32_e32 v16, v4, v16
	v_add_u32_e32 v17, v4, v17
	v_add_u32_e32 v18, v4, v18
	v_add_u32_e32 v19, v4, v19
	v_add_u32_e32 v20, v4, v20
	v_add_u32_e32 v21, v4, v21
	v_add_u32_e32 v22, v4, v22
	v_add_u32_e32 v23, v4, v23
	v_add_u32_e32 v24, v4, v24
	v_add_u32_e32 v25, v4, v25
	v_add_u32_e32 v26, v4, v26
	v_add_u32_e32 v27, v4, v27
	v_add_u32_e32 v28, v4, v28
	v_add_u32_e32 v29, v4, v29
	v_add_u32_e32 v30, v4, v30
	s_mov_b32 s13, 0xc3e00000
	v_mov_b32_e32 v31, 0x43e00000
	s_mov_b32 s14, s77
	v_readlane_b32 s9, v250, 1
	v_mov_b32_e32 v108, v8
	v_mov_b32_e32 v110, v10
	v_ashrrev_i32_e32 v104, 31, v108
	v_lshrrev_b32_e32 v104, 27, v104
	v_add_u32_e32 v104, v108, v104
	v_ashrrev_i32_e32 v132, 5, v104
	v_lshlrev_b32_e32 v104, 11, v132
	v_cmp_gt_i32_e64 s[98:99], s12, v108
	v_sub_u32_e32 v105, 0, v104
	v_lshlrev_b32_e32 v104, 6, v132
	s_and_saveexec_b64 s[100:101], s[98:99]
	s_cbranch_execz .Lpwt_4_a
	v_add_u32_e32 v133, v110, v105
	v_lshlrev_b32_e32 v132, 5, v132
	v_add_u32_e32 v134, v133, v6
	v_sub_u32_e32 v132, v108, v132
	v_and_b32_e32 v133, 0xffffff80, v133
	v_and_b32_e32 v135, 0x4c, v134
	v_or3_b32 v133, v9, v133, v135
	v_cmp_gt_i32_e64 s[0:1], 0, v132
	v_or_b32_e32 v140, v104, v1
	v_ashrrev_i32_e32 v141, 31, v140
	v_cndmask_b32_e64 v132, v134, v133, s[0:1]
	v_ashrrev_i32_e32 v133, 31, v132
	v_lshl_add_u64 v[142:143], v[132:133], 2, s[50:51]
	v_lshlrev_b64 v[132:133], 13, v[140:141]
	v_or_b32_e32 v134, 16, v140
	v_or_b32_e32 v144, 32, v140
	v_or_b32_e32 v140, 48, v140
	v_ashrrev_i32_e32 v135, 31, v134
	v_ashrrev_i32_e32 v145, 31, v144
	v_ashrrev_i32_e32 v141, 31, v140
	v_lshlrev_b64 v[134:135], 13, v[134:135]
	v_lshlrev_b64 v[144:145], 13, v[144:145]
	v_lshlrev_b64 v[140:141], 13, v[140:141]
	v_lshl_add_u64 v[132:133], v[142:143], 0, v[132:133]
	v_lshl_add_u64 v[136:137], v[142:143], 0, v[134:135]
	v_lshl_add_u64 v[144:145], v[142:143], 0, v[144:145]
	v_lshl_add_u64 v[146:147], v[142:143], 0, v[140:141]
	v_mov_b32_e32 v160, v132
	v_mov_b32_e32 v161, v133
	global_load_dwordx4 v[132:135], v[132:133], off
	s_nop 0
	global_load_dwordx4 v[136:139], v[136:137], off
	s_nop 0
	global_load_dwordx4 v[140:143], v[144:145], off
	s_nop 0
	global_load_dwordx4 v[144:147], v[146:147], off
	global_load_dword v162, v[160:161], off

.LBB0_140:
	v_ashrrev_i32_e32 v4, 31, v8
	v_lshrrev_b32_e32 v4, 27, v4
	v_add_u32_e32 v4, v8, v4
	v_ashrrev_i32_e32 v32, 5, v4
	v_lshlrev_b32_e32 v4, 11, v32
	v_cmp_gt_i32_e32 vcc, s12, v8
	v_sub_u32_e32 v5, 0, v4
	v_lshlrev_b32_e32 v4, 6, v32
	s_and_saveexec_b64 s[10:11], vcc
	s_cbranch_execz .LBB0_142
	s_waitcnt vmcnt(1)
	ds_write_b128 v11, v[132:135]
	ds_write_b128 v12, v[136:139]
	ds_write_b128 v13, v[140:143]
	ds_write_b128 v14, v[144:147]
	v_add_u32_e32 v108, s3, v8
	v_add_u32_e32 v110, s2, v10
	v_ashrrev_i32_e32 v104, 31, v108
	v_lshrrev_b32_e32 v104, 27, v104
	v_add_u32_e32 v104, v108, v104
	v_ashrrev_i32_e32 v132, 5, v104
	v_lshlrev_b32_e32 v104, 11, v132
	v_cmp_gt_i32_e64 s[98:99], s12, v108
	v_sub_u32_e32 v105, 0, v104
	v_lshlrev_b32_e32 v104, 6, v132
	s_and_saveexec_b64 s[100:101], s[98:99]
	s_cbranch_execz .Lpwt_4_b
	v_add_u32_e32 v133, v110, v105
	v_lshlrev_b32_e32 v132, 5, v132
	v_add_u32_e32 v134, v133, v6
	v_sub_u32_e32 v132, v108, v132
	v_and_b32_e32 v133, 0xffffff80, v133
	v_and_b32_e32 v135, 0x4c, v134
	v_or3_b32 v133, v9, v133, v135
	v_cmp_gt_i32_e64 s[0:1], 0, v132
	v_or_b32_e32 v140, v104, v1
	v_ashrrev_i32_e32 v141, 31, v140
	v_cndmask_b32_e64 v132, v134, v133, s[0:1]
	v_ashrrev_i32_e32 v133, 31, v132
	v_lshl_add_u64 v[142:143], v[132:133], 2, s[50:51]
	v_lshlrev_b64 v[132:133], 13, v[140:141]
	v_or_b32_e32 v134, 16, v140
	v_or_b32_e32 v144, 32, v140
	v_or_b32_e32 v140, 48, v140
	v_ashrrev_i32_e32 v135, 31, v134
	v_ashrrev_i32_e32 v145, 31, v144
	v_ashrrev_i32_e32 v141, 31, v140
	v_lshlrev_b64 v[134:135], 13, v[134:135]
	v_lshlrev_b64 v[144:145], 13, v[144:145]
	v_lshlrev_b64 v[140:141], 13, v[140:141]
	v_lshl_add_u64 v[132:133], v[142:143], 0, v[132:133]
	v_lshl_add_u64 v[136:137], v[142:143], 0, v[134:135]
	v_lshl_add_u64 v[144:145], v[142:143], 0, v[144:145]
	v_lshl_add_u64 v[146:147], v[142:143], 0, v[140:141]
	global_load_dwordx4 v[132:135], v[132:133], off
	s_nop 0
	global_load_dwordx4 v[136:139], v[136:137], off
	s_nop 0
	global_load_dwordx4 v[140:143], v[144:145], off
	s_nop 0
	global_load_dwordx4 v[144:147], v[146:147], off

.LBB0_144:
	v_mov_b32_e32 v3, v0
	s_and_b64 vcc, exec, s[72:73]
	s_cbranch_vccnz .LBB0_151
	s_add_u32 s6, s50, 0x1000000
	v_readlane_b32 s8, v250, 0
	s_addc_u32 s7, s51, 0
	v_readlane_b32 s10, v250, 2
	v_readlane_b32 s11, v250, 3
	s_add_u32 s0, s10, s4
	s_addc_u32 s1, s11, s5
	v_lshlrev_b32_e32 v2, 2, v3
	s_add_u32 s4, s0, 0x32be6000
	v_and_b32_e32 v6, 60, v2
	v_ashrrev_i32_e32 v2, 8, v3
	v_readlane_b32 s0, v250, 27
	v_lshl_add_u32 v4, v2, 16, 0
	v_lshlrev_b32_e32 v5, 1, v3
	v_add_u32_e32 v8, s0, v2
	v_lshlrev_b32_e32 v2, 4, v3
	v_and_b32_e32 v2, 48, v2
	v_bfe_u32 v1, v3, 4, 4
	v_bfe_u32 v7, v3, 2, 6
	v_and_b32_e32 v5, 16, v5
	v_lshlrev_b32_e32 v3, 3, v3
	v_mul_u32_u24_e32 v10, 0x44, v2
	v_and_or_b32 v9, v3, 32, v5
	v_mul_u32_u24_e32 v5, 0x44, v1
	v_or_b32_e32 v10, v10, v7
	v_add_lshl_u32 v5, v5, v6, 2
	v_lshlrev_b32_e32 v15, 2, v10
	v_add_u32_e32 v12, 0x1100, v5
	v_add_u32_e32 v13, 0x2200, v5
	v_add_u32_e32 v14, 0x3300, v5
	v_add_u32_e32 v16, 0x110, v15
	v_add_u32_e32 v17, 0x220, v15
	v_add_u32_e32 v18, 0x330, v15
	v_add_u32_e32 v19, 0x440, v15
	v_add_u32_e32 v20, 0x550, v15
	v_add_u32_e32 v21, 0x660, v15
	v_add_u32_e32 v22, 0x770, v15
	v_add_u32_e32 v23, 0x880, v15
	v_add_u32_e32 v24, 0x990, v15
	v_add_u32_e32 v25, 0xaa0, v15
	v_add_u32_e32 v26, 0xbb0, v15
	v_add_u32_e32 v27, 0xcc0, v15
	v_add_u32_e32 v28, 0xdd0, v15
	v_add_u32_e32 v29, 0xee0, v15
	v_add_u32_e32 v30, 0xff0, v15
	s_addc_u32 s5, s1, 0
	v_mov_b32_e32 v3, 0
	v_lshlrev_b32_e32 v10, 6, v8
	s_lshl_b32 s2, s3, 6
	s_movk_i32 s12, 0x400
	v_add_u32_e32 v11, v4, v5
	v_add_u32_e32 v12, v4, v12
	v_add_u32_e32 v13, v4, v13
	v_add_u32_e32 v14, v4, v14
	v_add_u32_e32 v15, v4, v15
	v_add_u32_e32 v16, v4, v16
	v_add_u32_e32 v17, v4, v17
	v_add_u32_e32 v18, v4, v18
	v_add_u32_e32 v19, v4, v19
	v_add_u32_e32 v20, v4, v20
	v_add_u32_e32 v21, v4, v21
	v_add_u32_e32 v22, v4, v22
	v_add_u32_e32 v23, v4, v23
	v_add_u32_e32 v24, v4, v24
	v_add_u32_e32 v25, v4, v25
	v_add_u32_e32 v26, v4, v26
	v_add_u32_e32 v27, v4, v27
	v_add_u32_e32 v28, v4, v28
	v_add_u32_e32 v29, v4, v29
	v_add_u32_e32 v30, v4, v30
	s_mov_b32 s13, 0xc3e00000
	v_mov_b32_e32 v31, 0x43e00000
	s_mov_b32 s14, s77
	v_readlane_b32 s9, v250, 1
	v_mov_b32_e32 v108, v8
	v_mov_b32_e32 v110, v10
	v_ashrrev_i32_e32 v104, 31, v108
	v_lshrrev_b32_e32 v104, 27, v104
	v_add_u32_e32 v104, v108, v104
	v_ashrrev_i32_e32 v132, 5, v104
	v_lshlrev_b32_e32 v104, 11, v132
	v_cmp_gt_i32_e64 s[98:99], s12, v108
	v_sub_u32_e32 v105, 0, v104
	v_lshlrev_b32_e32 v104, 6, v132
	s_and_saveexec_b64 s[100:101], s[98:99]
	s_cbranch_execz .Lpwt_5_a
	v_add_u32_e32 v133, v110, v105
	v_lshlrev_b32_e32 v132, 5, v132
	v_add_u32_e32 v134, v133, v6
	v_sub_u32_e32 v132, v108, v132
	v_and_b32_e32 v133, 0xffffff80, v133
	v_and_b32_e32 v135, 0x4c, v134
	v_or3_b32 v133, v9, v133, v135
	v_cmp_gt_i32_e64 s[0:1], 0, v132
	v_or_b32_e32 v140, v104, v1
	v_ashrrev_i32_e32 v141, 31, v140
	v_cndmask_b32_e64 v132, v134, v133, s[0:1]
	v_ashrrev_i32_e32 v133, 31, v132
	v_lshl_add_u64 v[142:143], v[132:133], 2, s[6:7]
	v_lshlrev_b64 v[132:133], 13, v[140:141]
	v_or_b32_e32 v134, 16, v140
	v_or_b32_e32 v144, 32, v140
	v_or_b32_e32 v140, 48, v140
	v_ashrrev_i32_e32 v135, 31, v134
	v_ashrrev_i32_e32 v145, 31, v144
	v_ashrrev_i32_e32 v141, 31, v140
	v_lshlrev_b64 v[134:135], 13, v[134:135]
	v_lshlrev_b64 v[144:145], 13, v[144:145]
	v_lshlrev_b64 v[140:141], 13, v[140:141]
	v_lshl_add_u64 v[132:133], v[142:143], 0, v[132:133]
	v_lshl_add_u64 v[136:137], v[142:143], 0, v[134:135]
	v_lshl_add_u64 v[144:145], v[142:143], 0, v[144:145]
	v_lshl_add_u64 v[146:147], v[142:143], 0, v[140:141]
	v_mov_b32_e32 v160, v132
	v_mov_b32_e32 v161, v133
	global_load_dwordx4 v[132:135], v[132:133], off
	s_nop 0
	global_load_dwordx4 v[136:139], v[136:137], off
	s_nop 0
	global_load_dwordx4 v[140:143], v[144:145], off
	s_nop 0
	global_load_dwordx4 v[144:147], v[146:147], off
	global_load_dword v162, v[160:161], off

.LBB0_147:
	v_ashrrev_i32_e32 v4, 31, v8
	v_lshrrev_b32_e32 v4, 27, v4
	v_add_u32_e32 v4, v8, v4
	v_ashrrev_i32_e32 v32, 5, v4
	v_lshlrev_b32_e32 v4, 11, v32
	v_cmp_gt_i32_e32 vcc, s12, v8
	v_sub_u32_e32 v5, 0, v4
	v_lshlrev_b32_e32 v4, 6, v32
	s_and_saveexec_b64 s[10:11], vcc
	s_cbranch_execz .LBB0_149
	s_waitcnt vmcnt(1)
	ds_write_b128 v11, v[132:135]
	ds_write_b128 v12, v[136:139]
	ds_write_b128 v13, v[140:143]
	ds_write_b128 v14, v[144:147]
	v_add_u32_e32 v108, s3, v8
	v_add_u32_e32 v110, s2, v10
	v_ashrrev_i32_e32 v104, 31, v108
	v_lshrrev_b32_e32 v104, 27, v104
	v_add_u32_e32 v104, v108, v104
	v_ashrrev_i32_e32 v132, 5, v104
	v_lshlrev_b32_e32 v104, 11, v132
	v_cmp_gt_i32_e64 s[98:99], s12, v108
	v_sub_u32_e32 v105, 0, v104
	v_lshlrev_b32_e32 v104, 6, v132
	s_and_saveexec_b64 s[100:101], s[98:99]
	s_cbranch_execz .Lpwt_5_b
	v_add_u32_e32 v133, v110, v105
	v_lshlrev_b32_e32 v132, 5, v132
	v_add_u32_e32 v134, v133, v6
	v_sub_u32_e32 v132, v108, v132
	v_and_b32_e32 v133, 0xffffff80, v133
	v_and_b32_e32 v135, 0x4c, v134
	v_or3_b32 v133, v9, v133, v135
	v_cmp_gt_i32_e64 s[0:1], 0, v132
	v_or_b32_e32 v140, v104, v1
	v_ashrrev_i32_e32 v141, 31, v140
	v_cndmask_b32_e64 v132, v134, v133, s[0:1]
	v_ashrrev_i32_e32 v133, 31, v132
	v_lshl_add_u64 v[142:143], v[132:133], 2, s[6:7]
	v_lshlrev_b64 v[132:133], 13, v[140:141]
	v_or_b32_e32 v134, 16, v140
	v_or_b32_e32 v144, 32, v140
	v_or_b32_e32 v140, 48, v140
	v_ashrrev_i32_e32 v135, 31, v134
	v_ashrrev_i32_e32 v145, 31, v144
	v_ashrrev_i32_e32 v141, 31, v140
	v_lshlrev_b64 v[134:135], 13, v[134:135]
	v_lshlrev_b64 v[144:145], 13, v[144:145]
	v_lshlrev_b64 v[140:141], 13, v[140:141]
	v_lshl_add_u64 v[132:133], v[142:143], 0, v[132:133]
	v_lshl_add_u64 v[136:137], v[142:143], 0, v[134:135]
	v_lshl_add_u64 v[144:145], v[142:143], 0, v[144:145]
	v_lshl_add_u64 v[146:147], v[142:143], 0, v[140:141]
	global_load_dwordx4 v[132:135], v[132:133], off
	s_nop 0
	global_load_dwordx4 v[136:139], v[136:137], off
	s_nop 0
	global_load_dwordx4 v[140:143], v[144:145], off
	s_nop 0
	global_load_dwordx4 v[144:147], v[146:147], off

.LBB0_151:
	v_mov_b32_e32 v3, v0
	s_mov_b64 s[4:5], 0
	s_mov_b64 s[0:1], 0
	s_and_b64 vcc, exec, s[72:73]
	s_cbranch_vccnz .LBB0_158
	s_add_u32 s6, s50, 0x2000000
	v_readlane_b32 s8, v250, 0
	s_addc_u32 s7, s51, 0
	v_readlane_b32 s10, v250, 2
	v_readlane_b32 s11, v250, 3
	s_add_u32 s0, s10, s0
	s_addc_u32 s1, s11, s1
	v_lshlrev_b32_e32 v2, 2, v3
	s_add_u32 s10, s0, 0x32fe6000
	v_and_b32_e32 v6, 60, v2
	v_ashrrev_i32_e32 v2, 8, v3
	v_readlane_b32 s0, v250, 27
	v_lshl_add_u32 v4, v2, 16, 0
	v_lshlrev_b32_e32 v5, 1, v3
	v_add_u32_e32 v8, s0, v2
	v_lshlrev_b32_e32 v2, 4, v3
	v_and_b32_e32 v2, 48, v2
	v_bfe_u32 v1, v3, 4, 4
	v_bfe_u32 v7, v3, 2, 6
	v_and_b32_e32 v5, 16, v5
	v_lshlrev_b32_e32 v3, 3, v3
	v_mul_u32_u24_e32 v10, 0x44, v2
	v_and_or_b32 v9, v3, 32, v5
	v_mul_u32_u24_e32 v5, 0x44, v1
	v_or_b32_e32 v10, v10, v7
	v_add_lshl_u32 v5, v5, v6, 2
	v_lshlrev_b32_e32 v15, 2, v10
	v_add_u32_e32 v12, 0x1100, v5
	v_add_u32_e32 v13, 0x2200, v5
	v_add_u32_e32 v14, 0x3300, v5
	v_add_u32_e32 v16, 0x110, v15
	v_add_u32_e32 v17, 0x220, v15
	v_add_u32_e32 v18, 0x330, v15
	v_add_u32_e32 v19, 0x440, v15
	v_add_u32_e32 v20, 0x550, v15
	v_add_u32_e32 v21, 0x660, v15
	v_add_u32_e32 v22, 0x770, v15
	v_add_u32_e32 v23, 0x880, v15
	v_add_u32_e32 v24, 0x990, v15
	v_add_u32_e32 v25, 0xaa0, v15
	v_add_u32_e32 v26, 0xbb0, v15
	v_add_u32_e32 v27, 0xcc0, v15
	v_add_u32_e32 v28, 0xdd0, v15
	v_add_u32_e32 v29, 0xee0, v15
	v_add_u32_e32 v30, 0xff0, v15
	s_addc_u32 s11, s1, 0
	v_mov_b32_e32 v3, 0
	v_lshlrev_b32_e32 v10, 6, v8
	s_lshl_b32 s2, s3, 6
	s_movk_i32 s14, 0x400
	v_add_u32_e32 v11, v4, v5
	v_add_u32_e32 v12, v4, v12
	v_add_u32_e32 v13, v4, v13
	v_add_u32_e32 v14, v4, v14
	v_add_u32_e32 v15, v4, v15
	v_add_u32_e32 v16, v4, v16
	v_add_u32_e32 v17, v4, v17
	v_add_u32_e32 v18, v4, v18
	v_add_u32_e32 v19, v4, v19
	v_add_u32_e32 v20, v4, v20
	v_add_u32_e32 v21, v4, v21
	v_add_u32_e32 v22, v4, v22
	v_add_u32_e32 v23, v4, v23
	v_add_u32_e32 v24, v4, v24
	v_add_u32_e32 v25, v4, v25
	v_add_u32_e32 v26, v4, v26
	v_add_u32_e32 v27, v4, v27
	v_add_u32_e32 v28, v4, v28
	v_add_u32_e32 v29, v4, v29
	v_add_u32_e32 v30, v4, v30
	s_mov_b32 s15, 0xc3e00000
	v_mov_b32_e32 v31, 0x43e00000
	s_mov_b32 s16, s77
	v_readlane_b32 s9, v250, 1
	v_mov_b32_e32 v108, v8
	v_mov_b32_e32 v110, v10
	v_ashrrev_i32_e32 v104, 31, v108
	v_lshrrev_b32_e32 v104, 27, v104
	v_add_u32_e32 v104, v108, v104
	v_ashrrev_i32_e32 v132, 5, v104
	v_lshlrev_b32_e32 v104, 11, v132
	v_cmp_gt_i32_e64 s[98:99], s14, v108
	v_sub_u32_e32 v105, 0, v104
	v_lshlrev_b32_e32 v104, 6, v132
	s_and_saveexec_b64 s[100:101], s[98:99]
	s_cbranch_execz .Lpwt_6_a
	v_add_u32_e32 v133, v110, v105
	v_lshlrev_b32_e32 v132, 5, v132
	v_add_u32_e32 v134, v133, v6
	v_sub_u32_e32 v132, v108, v132
	v_and_b32_e32 v133, 0xffffff80, v133
	v_and_b32_e32 v135, 0x4c, v134
	v_or3_b32 v133, v9, v133, v135
	v_cmp_gt_i32_e64 s[0:1], 0, v132
	v_or_b32_e32 v140, v104, v1
	v_ashrrev_i32_e32 v141, 31, v140
	v_cndmask_b32_e64 v132, v134, v133, s[0:1]
	v_ashrrev_i32_e32 v133, 31, v132
	v_lshl_add_u64 v[142:143], v[132:133], 2, s[6:7]
	v_lshlrev_b64 v[132:133], 13, v[140:141]
	v_or_b32_e32 v134, 16, v140
	v_or_b32_e32 v144, 32, v140
	v_or_b32_e32 v140, 48, v140
	v_ashrrev_i32_e32 v135, 31, v134
	v_ashrrev_i32_e32 v145, 31, v144
	v_ashrrev_i32_e32 v141, 31, v140
	v_lshlrev_b64 v[134:135], 13, v[134:135]
	v_lshlrev_b64 v[144:145], 13, v[144:145]
	v_lshlrev_b64 v[140:141], 13, v[140:141]
	v_lshl_add_u64 v[132:133], v[142:143], 0, v[132:133]
	v_lshl_add_u64 v[136:137], v[142:143], 0, v[134:135]
	v_lshl_add_u64 v[144:145], v[142:143], 0, v[144:145]
	v_lshl_add_u64 v[146:147], v[142:143], 0, v[140:141]
	v_mov_b32_e32 v160, v132
	v_mov_b32_e32 v161, v133
	global_load_dwordx4 v[132:135], v[132:133], off
	s_nop 0
	global_load_dwordx4 v[136:139], v[136:137], off
	s_nop 0
	global_load_dwordx4 v[140:143], v[144:145], off
	s_nop 0
	global_load_dwordx4 v[144:147], v[146:147], off
	global_load_dword v162, v[160:161], off

.LBB0_154:
	v_ashrrev_i32_e32 v4, 31, v8
	v_lshrrev_b32_e32 v4, 27, v4
	v_add_u32_e32 v4, v8, v4
	v_ashrrev_i32_e32 v32, 5, v4
	v_lshlrev_b32_e32 v4, 11, v32
	v_cmp_gt_i32_e32 vcc, s14, v8
	v_sub_u32_e32 v5, 0, v4
	v_lshlrev_b32_e32 v4, 6, v32
	s_and_saveexec_b64 s[12:13], vcc
	s_cbranch_execz .LBB0_156
	s_waitcnt vmcnt(1)
	ds_write_b128 v11, v[132:135]
	ds_write_b128 v12, v[136:139]
	ds_write_b128 v13, v[140:143]
	ds_write_b128 v14, v[144:147]
	v_add_u32_e32 v108, s3, v8
	v_add_u32_e32 v110, s2, v10
	v_ashrrev_i32_e32 v104, 31, v108
	v_lshrrev_b32_e32 v104, 27, v104
	v_add_u32_e32 v104, v108, v104
	v_ashrrev_i32_e32 v132, 5, v104
	v_lshlrev_b32_e32 v104, 11, v132
	v_cmp_gt_i32_e64 s[98:99], s14, v108
	v_sub_u32_e32 v105, 0, v104
	v_lshlrev_b32_e32 v104, 6, v132
	s_and_saveexec_b64 s[100:101], s[98:99]
	s_cbranch_execz .Lpwt_6_b
	v_add_u32_e32 v133, v110, v105
	v_lshlrev_b32_e32 v132, 5, v132
	v_add_u32_e32 v134, v133, v6
	v_sub_u32_e32 v132, v108, v132
	v_and_b32_e32 v133, 0xffffff80, v133
	v_and_b32_e32 v135, 0x4c, v134
	v_or3_b32 v133, v9, v133, v135
	v_cmp_gt_i32_e64 s[0:1], 0, v132
	v_or_b32_e32 v140, v104, v1
	v_ashrrev_i32_e32 v141, 31, v140
	v_cndmask_b32_e64 v132, v134, v133, s[0:1]
	v_ashrrev_i32_e32 v133, 31, v132
	v_lshl_add_u64 v[142:143], v[132:133], 2, s[6:7]
	v_lshlrev_b64 v[132:133], 13, v[140:141]
	v_or_b32_e32 v134, 16, v140
	v_or_b32_e32 v144, 32, v140
	v_or_b32_e32 v140, 48, v140
	v_ashrrev_i32_e32 v135, 31, v134
	v_ashrrev_i32_e32 v145, 31, v144
	v_ashrrev_i32_e32 v141, 31, v140
	v_lshlrev_b64 v[134:135], 13, v[134:135]
	v_lshlrev_b64 v[144:145], 13, v[144:145]
	v_lshlrev_b64 v[140:141], 13, v[140:141]
	v_lshl_add_u64 v[132:133], v[142:143], 0, v[132:133]
	v_lshl_add_u64 v[136:137], v[142:143], 0, v[134:135]
	v_lshl_add_u64 v[144:145], v[142:143], 0, v[144:145]
	v_lshl_add_u64 v[146:147], v[142:143], 0, v[140:141]
	global_load_dwordx4 v[132:135], v[132:133], off
	s_nop 0
	global_load_dwordx4 v[136:139], v[136:137], off
	s_nop 0
	global_load_dwordx4 v[140:143], v[144:145], off
	s_nop 0
	global_load_dwordx4 v[144:147], v[146:147], off

.LBB0_158:
	v_mov_b32_e32 v3, v0
	s_and_b64 vcc, exec, s[72:73]
	s_cbranch_vccnz .LBB0_165
	s_add_u32 s6, s50, 0x3000000
	v_readlane_b32 s8, v250, 0
	s_addc_u32 s7, s51, 0
	v_readlane_b32 s10, v250, 2
	v_readlane_b32 s11, v250, 3
	s_add_u32 s0, s10, s4
	s_addc_u32 s1, s11, s5
	v_lshlrev_b32_e32 v2, 2, v3
	s_add_u32 s4, s0, 0x333e6000
	v_and_b32_e32 v6, 60, v2
	v_ashrrev_i32_e32 v2, 8, v3
	v_readlane_b32 s0, v250, 27
	v_lshl_add_u32 v4, v2, 16, 0
	v_lshlrev_b32_e32 v5, 1, v3
	v_add_u32_e32 v8, s0, v2
	v_lshlrev_b32_e32 v2, 4, v3
	v_and_b32_e32 v2, 48, v2
	v_bfe_u32 v1, v3, 4, 4
	v_bfe_u32 v7, v3, 2, 6
	v_and_b32_e32 v5, 16, v5
	v_lshlrev_b32_e32 v3, 3, v3
	v_mul_u32_u24_e32 v10, 0x44, v2
	v_and_or_b32 v9, v3, 32, v5
	v_mul_u32_u24_e32 v5, 0x44, v1
	v_or_b32_e32 v10, v10, v7
	v_add_lshl_u32 v5, v5, v6, 2
	v_lshlrev_b32_e32 v15, 2, v10
	v_add_u32_e32 v12, 0x1100, v5
	v_add_u32_e32 v13, 0x2200, v5
	v_add_u32_e32 v14, 0x3300, v5
	v_add_u32_e32 v16, 0x110, v15
	v_add_u32_e32 v17, 0x220, v15
	v_add_u32_e32 v18, 0x330, v15
	v_add_u32_e32 v19, 0x440, v15
	v_add_u32_e32 v20, 0x550, v15
	v_add_u32_e32 v21, 0x660, v15
	v_add_u32_e32 v22, 0x770, v15
	v_add_u32_e32 v23, 0x880, v15
	v_add_u32_e32 v24, 0x990, v15
	v_add_u32_e32 v25, 0xaa0, v15
	v_add_u32_e32 v26, 0xbb0, v15
	v_add_u32_e32 v27, 0xcc0, v15
	v_add_u32_e32 v28, 0xdd0, v15
	v_add_u32_e32 v29, 0xee0, v15
	v_add_u32_e32 v30, 0xff0, v15
	s_addc_u32 s5, s1, 0
	v_mov_b32_e32 v3, 0
	v_lshlrev_b32_e32 v10, 6, v8
	s_lshl_b32 s2, s3, 6
	s_movk_i32 s10, 0x400
	v_add_u32_e32 v11, v4, v5
	v_add_u32_e32 v12, v4, v12
	v_add_u32_e32 v13, v4, v13
	v_add_u32_e32 v14, v4, v14
	v_add_u32_e32 v15, v4, v15
	v_add_u32_e32 v16, v4, v16
	v_add_u32_e32 v17, v4, v17
	v_add_u32_e32 v18, v4, v18
	v_add_u32_e32 v19, v4, v19
	v_add_u32_e32 v20, v4, v20
	v_add_u32_e32 v21, v4, v21
	v_add_u32_e32 v22, v4, v22
	v_add_u32_e32 v23, v4, v23
	v_add_u32_e32 v24, v4, v24
	v_add_u32_e32 v25, v4, v25
	v_add_u32_e32 v26, v4, v26
	v_add_u32_e32 v27, v4, v27
	v_add_u32_e32 v28, v4, v28
	v_add_u32_e32 v29, v4, v29
	v_add_u32_e32 v30, v4, v30
	s_mov_b32 s11, 0xc3e00000
	v_mov_b32_e32 v31, 0x43e00000
	v_readlane_b32 s9, v250, 1
	v_mov_b32_e32 v108, v8
	v_mov_b32_e32 v110, v10
	v_ashrrev_i32_e32 v104, 31, v108
	v_lshrrev_b32_e32 v104, 27, v104
	v_add_u32_e32 v104, v108, v104
	v_ashrrev_i32_e32 v132, 5, v104
	v_lshlrev_b32_e32 v104, 11, v132
	v_cmp_gt_i32_e64 s[98:99], s10, v108
	v_sub_u32_e32 v105, 0, v104
	v_lshlrev_b32_e32 v104, 6, v132
	s_and_saveexec_b64 s[100:101], s[98:99]
	s_cbranch_execz .Lpwt_7_a
	v_add_u32_e32 v133, v110, v105
	v_lshlrev_b32_e32 v132, 5, v132
	v_add_u32_e32 v134, v133, v6
	v_sub_u32_e32 v132, v108, v132
	v_and_b32_e32 v133, 0xffffff80, v133
	v_and_b32_e32 v135, 0x4c, v134
	v_or3_b32 v133, v9, v133, v135
	v_cmp_gt_i32_e64 s[0:1], 0, v132
	v_or_b32_e32 v140, v104, v1
	v_ashrrev_i32_e32 v141, 31, v140
	v_cndmask_b32_e64 v132, v134, v133, s[0:1]
	v_ashrrev_i32_e32 v133, 31, v132
	v_lshl_add_u64 v[142:143], v[132:133], 2, s[6:7]
	v_lshlrev_b64 v[132:133], 13, v[140:141]
	v_or_b32_e32 v134, 16, v140
	v_or_b32_e32 v144, 32, v140
	v_or_b32_e32 v140, 48, v140
	v_ashrrev_i32_e32 v135, 31, v134
	v_ashrrev_i32_e32 v145, 31, v144
	v_ashrrev_i32_e32 v141, 31, v140
	v_lshlrev_b64 v[134:135], 13, v[134:135]
	v_lshlrev_b64 v[144:145], 13, v[144:145]
	v_lshlrev_b64 v[140:141], 13, v[140:141]
	v_lshl_add_u64 v[132:133], v[142:143], 0, v[132:133]
	v_lshl_add_u64 v[136:137], v[142:143], 0, v[134:135]
	v_lshl_add_u64 v[144:145], v[142:143], 0, v[144:145]
	v_lshl_add_u64 v[146:147], v[142:143], 0, v[140:141]
	v_mov_b32_e32 v160, v132
	v_mov_b32_e32 v161, v133
	global_load_dwordx4 v[132:135], v[132:133], off
	s_nop 0
	global_load_dwordx4 v[136:139], v[136:137], off
	s_nop 0
	global_load_dwordx4 v[140:143], v[144:145], off
	s_nop 0
	global_load_dwordx4 v[144:147], v[146:147], off
	global_load_dword v162, v[160:161], off

.LBB0_161:
	v_ashrrev_i32_e32 v4, 31, v8
	v_lshrrev_b32_e32 v4, 27, v4
	v_add_u32_e32 v4, v8, v4
	v_ashrrev_i32_e32 v32, 5, v4
	v_lshlrev_b32_e32 v4, 11, v32
	v_cmp_gt_i32_e32 vcc, s10, v8
	v_sub_u32_e32 v5, 0, v4
	v_lshlrev_b32_e32 v4, 6, v32
	s_and_saveexec_b64 s[8:9], vcc
	s_cbranch_execz .LBB0_163
	s_waitcnt vmcnt(1)
	ds_write_b128 v11, v[132:135]
	ds_write_b128 v12, v[136:139]
	ds_write_b128 v13, v[140:143]
	ds_write_b128 v14, v[144:147]
	v_add_u32_e32 v108, s3, v8
	v_add_u32_e32 v110, s2, v10
	v_ashrrev_i32_e32 v104, 31, v108
	v_lshrrev_b32_e32 v104, 27, v104
	v_add_u32_e32 v104, v108, v104
	v_ashrrev_i32_e32 v132, 5, v104
	v_lshlrev_b32_e32 v104, 11, v132
	v_cmp_gt_i32_e64 s[98:99], s10, v108
	v_sub_u32_e32 v105, 0, v104
	v_lshlrev_b32_e32 v104, 6, v132
	s_and_saveexec_b64 s[100:101], s[98:99]
	s_cbranch_execz .Lpwt_7_b
	v_add_u32_e32 v133, v110, v105
	v_lshlrev_b32_e32 v132, 5, v132
	v_add_u32_e32 v134, v133, v6
	v_sub_u32_e32 v132, v108, v132
	v_and_b32_e32 v133, 0xffffff80, v133
	v_and_b32_e32 v135, 0x4c, v134
	v_or3_b32 v133, v9, v133, v135
	v_cmp_gt_i32_e64 s[0:1], 0, v132
	v_or_b32_e32 v140, v104, v1
	v_ashrrev_i32_e32 v141, 31, v140
	v_cndmask_b32_e64 v132, v134, v133, s[0:1]
	v_ashrrev_i32_e32 v133, 31, v132
	v_lshl_add_u64 v[142:143], v[132:133], 2, s[6:7]
	v_lshlrev_b64 v[132:133], 13, v[140:141]
	v_or_b32_e32 v134, 16, v140
	v_or_b32_e32 v144, 32, v140
	v_or_b32_e32 v140, 48, v140
	v_ashrrev_i32_e32 v135, 31, v134
	v_ashrrev_i32_e32 v145, 31, v144
	v_ashrrev_i32_e32 v141, 31, v140
	v_lshlrev_b64 v[134:135], 13, v[134:135]
	v_lshlrev_b64 v[144:145], 13, v[144:145]
	v_lshlrev_b64 v[140:141], 13, v[140:141]
	v_lshl_add_u64 v[132:133], v[142:143], 0, v[132:133]
	v_lshl_add_u64 v[136:137], v[142:143], 0, v[134:135]
	v_lshl_add_u64 v[144:145], v[142:143], 0, v[144:145]
	v_lshl_add_u64 v[146:147], v[142:143], 0, v[140:141]
	global_load_dwordx4 v[132:135], v[132:133], off
	s_nop 0
	global_load_dwordx4 v[136:139], v[136:137], off
	s_nop 0
	global_load_dwordx4 v[140:143], v[144:145], off
	s_nop 0
	global_load_dwordx4 v[144:147], v[146:147], off

	.amdhsa_kernel _Z8mega_fwd6Params
		.amdhsa_group_segment_fixed_size 0
		.amdhsa_private_segment_fixed_size 0
		.amdhsa_kernarg_size 496
		.amdhsa_user_sgpr_count 2
		.amdhsa_user_sgpr_dispatch_ptr 0
		.amdhsa_user_sgpr_queue_ptr 0
		.amdhsa_user_sgpr_kernarg_segment_ptr 1
		.amdhsa_user_sgpr_dispatch_id 0
		.amdhsa_user_sgpr_kernarg_preload_length 0
		.amdhsa_user_sgpr_kernarg_preload_offset 0
		.amdhsa_user_sgpr_private_segment_size 0
		.amdhsa_uses_dynamic_stack 0
		.amdhsa_enable_private_segment 0
		.amdhsa_system_sgpr_workgroup_id_x 1
		.amdhsa_system_sgpr_workgroup_id_y 0
		.amdhsa_system_sgpr_workgroup_id_z 0
		.amdhsa_system_sgpr_workgroup_info 0
		.amdhsa_system_vgpr_workitem_id 0
		.amdhsa_next_free_vgpr 251
		.amdhsa_next_free_sgpr 102
		.amdhsa_accum_offset 252
		.amdhsa_reserve_vcc 1
		.amdhsa_float_round_mode_32 0
		.amdhsa_float_round_mode_16_64 0
		.amdhsa_float_denorm_mode_32 3
		.amdhsa_float_denorm_mode_16_64 3
		.amdhsa_dx10_clamp 1
		.amdhsa_ieee_mode 1
		.amdhsa_fp16_overflow 0
		.amdhsa_tg_split 0
		.amdhsa_exception_fp_ieee_invalid_op 0
		.amdhsa_exception_fp_denorm_src 0
		.amdhsa_exception_fp_ieee_div_zero 0
		.amdhsa_exception_fp_ieee_overflow 0
		.amdhsa_exception_fp_ieee_underflow 0
		.amdhsa_exception_fp_ieee_inexact 0
		.amdhsa_exception_int_div_zero 0
	.end_amdhsa_kernel

amdhsa.kernels:
  - .agpr_count:     0
    .args:
      - .offset:         0
        .size:           240
        .value_kind:     by_value
      - .offset:         240
        .size:           4
        .value_kind:     hidden_block_count_x
      - .offset:         244
        .size:           4
        .value_kind:     hidden_block_count_y
      - .offset:         248
        .size:           4
        .value_kind:     hidden_block_count_z
      - .offset:         252
        .size:           2
        .value_kind:     hidden_group_size_x
      - .offset:         254
        .size:           2
        .value_kind:     hidden_group_size_y
      - .offset:         256
        .size:           2
        .value_kind:     hidden_group_size_z
      - .offset:         258
        .size:           2
        .value_kind:     hidden_remainder_x
      - .offset:         260
        .size:           2
        .value_kind:     hidden_remainder_y
      - .offset:         262
        .size:           2
        .value_kind:     hidden_remainder_z
      - .offset:         280
        .size:           8
        .value_kind:     hidden_global_offset_x
      - .offset:         288
        .size:           8
        .value_kind:     hidden_global_offset_y
      - .offset:         296
        .size:           8
        .value_kind:     hidden_global_offset_z
      - .offset:         304
        .size:           2
        .value_kind:     hidden_grid_dims
      - .offset:         360
        .size:           4
        .value_kind:     hidden_dynamic_lds_size
    .group_segment_fixed_size: 0
    .kernarg_segment_align: 8
    .kernarg_segment_size: 496
    .language:       OpenCL C
    .language_version:
      - 2
      - 0
    .max_flat_workgroup_size: 512
    .name:           _Z8mega_fwd6Params
    .private_segment_fixed_size: 0
    .sgpr_count:     108
    .sgpr_spill_count: 66
    .symbol:         _Z8mega_fwd6Params.kd
    .uniform_work_group_size: 1
    .uses_dynamic_stack: false
    .vgpr_count:     251
    .vgpr_spill_count: 0
    .wavefront_size: 64
